# v31: v30 plus hoisted attention tile loads with leaner 64-bit addressing and the redundant post-QK pads removed
# speedup vs baseline: 1.0263x; 1.0012x over previous
.Lattn_ldA_skip:
	s_or_b64 exec, exec, s[14:15]
	s_nop 1
	ds_read_b128 v[188:191], v181 offset:12288
	ds_read_b128 v[196:199], v181 offset:18432
	ds_read_b128 v[192:195], v182 offset:12288
	ds_read_b128 v[200:203], v182 offset:18432
	v_add_f32_e32 v2, 0, v150
	v_add_f32_e32 v2, v151, v2
	v_add_f32_e32 v2, v152, v2
	v_add_f32_e32 v2, v153, v2
	s_waitcnt lgkmcnt(1)
	v_mfma_scale_f32_32x32x64_f8f6f4 v[84:99], v[188:195], v[116:123], 0, v170, v170 op_sel_hi:[0,0,0]
	s_waitcnt lgkmcnt(0)
	v_mfma_scale_f32_32x32x64_f8f6f4 v[68:83], v[196:203], v[116:123], 0, v170, v170 op_sel_hi:[0,0,0]
	ds_read_b128 v[188:191], v181 offset:12352
	ds_read_b128 v[196:199], v181 offset:18496
	ds_read_b128 v[192:195], v182 offset:12352
	ds_read_b128 v[200:203], v182 offset:18496
	v_add_f32_e32 v2, v154, v2
	v_add_f32_e32 v2, v165, v2
	v_add_f32_e32 v2, v166, v2
	v_add_f32_e32 v2, v168, v2
	v_add_f32_e32 v2, v145, v2
	s_waitcnt lgkmcnt(1)
	v_mfma_scale_f32_32x32x64_f8f6f4 v[84:99], v[188:195], v[108:115], v[84:99], v170, v170 op_sel_hi:[0,0,0]
	s_waitcnt lgkmcnt(0)
	v_mfma_scale_f32_32x32x64_f8f6f4 v[68:83], v[196:203], v[108:115], v[68:83], v170, v170 op_sel_hi:[0,0,0]
	ds_read_b128 v[188:191], v181 offset:12416
	ds_read_b128 v[196:199], v181 offset:18560
	ds_read_b128 v[192:195], v182 offset:12416
	ds_read_b128 v[200:203], v182 offset:18560
	v_add_f32_e32 v2, v146, v2
	v_add_f32_e32 v2, v147, v2
	v_add_f32_e32 v2, v148, v2
	v_exp_f32_e32 v169, v140
	v_add_f32_e32 v2, v149, v2
	s_waitcnt lgkmcnt(1)
	v_mfma_scale_f32_32x32x64_f8f6f4 v[84:99], v[188:195], v[100:107], v[84:99], v170, v170 op_sel_hi:[0,0,0]
	v_exp_f32_e32 v188, v141
	v_add_f32_e32 v2, v155, v2
	v_exp_f32_e32 v136, v136
	v_add_f32_e32 v2, v164, v2
	v_exp_f32_e32 v137, v137
	v_add_f32_e32 v2, v167, v2
	v_exp_f32_e32 v134, v134
	v_add_f32_e32 v2, v169, v2
	v_exp_f32_e32 v135, v135
	v_add_f32_e32 v2, v188, v2
	v_exp_f32_e32 v130, v130
	v_add_f32_e32 v2, v136, v2
	v_exp_f32_e32 v131, v131
	v_add_f32_e32 v2, v137, v2
	v_exp_f32_e32 v128, v128
	v_add_f32_e32 v2, v134, v2
	v_exp_f32_e32 v129, v129
	v_add_f32_e32 v2, v135, v2
	v_exp_f32_e32 v189, v142
	v_add_f32_e32 v2, v130, v2
	v_exp_f32_e32 v190, v143
	v_add_f32_e32 v2, v131, v2
	v_exp_f32_e32 v138, v138
	v_add_f32_e32 v2, v128, v2
	v_exp_f32_e32 v139, v139
	v_add_f32_e32 v2, v129, v2
	v_exp_f32_e32 v132, v132
	v_add_f32_e32 v2, v189, v2
	v_exp_f32_e32 v133, v133
	v_add_f32_e32 v2, v190, v2
	v_add_f32_e32 v2, v138, v2
	v_add_f32_e32 v2, v139, v2
	v_add_f32_e32 v2, v132, v2
	v_add_f32_e32 v2, v133, v2
	v_mov_b32_e32 v187, v2
	v_cvt_pk_bf16_f32 v140, v150, v151
	v_cvt_pk_bf16_f32 v141, v152, v153
	v_cvt_pk_bf16_f32 v142, v154, v165
	v_cvt_pk_bf16_f32 v143, v166, v168
	v_cvt_pk_bf16_f32 v144, v145, v146
	v_cvt_pk_bf16_f32 v145, v147, v148
	v_cvt_pk_bf16_f32 v146, v149, v155
	v_cvt_pk_bf16_f32 v147, v164, v167
	v_cvt_pk_bf16_f32 v148, v169, v188
	v_cvt_pk_bf16_f32 v149, v136, v137
	v_cvt_pk_bf16_f32 v150, v134, v135
	v_cvt_pk_bf16_f32 v151, v130, v131
	v_cvt_pk_bf16_f32 v152, v128, v129
	v_cvt_pk_bf16_f32 v153, v189, v190
	v_cvt_pk_bf16_f32 v154, v138, v139
	v_cvt_pk_bf16_f32 v155, v132, v133
	s_waitcnt lgkmcnt(0)
	v_mfma_scale_f32_32x32x64_f8f6f4 v[68:83], v[196:203], v[100:107], v[68:83], v170, v170 op_sel_hi:[0,0,0]
	v_permlane32_swap_b32_e32 v2, v187
	v_permlane32_swap_b32_e32 v140, v142
	v_permlane32_swap_b32_e32 v141, v143
	v_permlane32_swap_b32_e32 v144, v146
	v_permlane32_swap_b32_e32 v145, v147
	v_permlane32_swap_b32_e32 v148, v150
	v_permlane32_swap_b32_e32 v149, v151
	v_permlane32_swap_b32_e32 v152, v154
	v_permlane32_swap_b32_e32 v153, v155
	ds_read_b64_tr_b16 v[188:189], v178 offset:0
	ds_read_b64_tr_b16 v[190:191], v178 offset:0x800
	ds_read_b64_tr_b16 v[192:193], v178 offset:0x1000
	ds_read_b64_tr_b16 v[194:195], v178 offset:0x1800
	ds_read_b64_tr_b16 v[196:197], v178 offset:0x2000
	ds_read_b64_tr_b16 v[198:199], v178 offset:0x2800
	ds_read_b64_tr_b16 v[200:201], v178 offset:0x3000
	ds_read_b64_tr_b16 v[202:203], v178 offset:0x3800
	s_waitcnt lgkmcnt(0)
	s_nop 0
	v_mfma_f32_32x32x16_bf16 v[52:67], v[140:143], v[188:191], v[52:67]
	ds_read_b64_tr_b16 v[188:189], v178 offset:0x200
	ds_read_b64_tr_b16 v[190:191], v178 offset:0xa00
	v_mfma_f32_32x32x16_bf16 v[52:67], v[144:147], v[192:195], v[52:67]
	ds_read_b64_tr_b16 v[192:193], v178 offset:0x1200
	ds_read_b64_tr_b16 v[194:195], v178 offset:0x1a00
	v_mfma_f32_32x32x16_bf16 v[52:67], v[148:151], v[196:199], v[52:67]
	ds_read_b64_tr_b16 v[196:197], v178 offset:0x2200
	ds_read_b64_tr_b16 v[198:199], v178 offset:0x2a00
	v_mfma_f32_32x32x16_bf16 v[52:67], v[152:155], v[200:203], v[52:67]
	ds_read_b64_tr_b16 v[200:201], v178 offset:0x3200
	ds_read_b64_tr_b16 v[202:203], v178 offset:0x3a00
	s_waitcnt lgkmcnt(0)
	v_mfma_f32_32x32x16_bf16 v[36:51], v[140:143], v[188:191], v[36:51]
	ds_read_b64_tr_b16 v[188:189], v178 offset:0x400
	ds_read_b64_tr_b16 v[190:191], v178 offset:0xc00
	v_mfma_f32_32x32x16_bf16 v[36:51], v[144:147], v[192:195], v[36:51]
	ds_read_b64_tr_b16 v[192:193], v178 offset:0x1400
	ds_read_b64_tr_b16 v[194:195], v178 offset:0x1c00
	v_mfma_f32_32x32x16_bf16 v[36:51], v[148:151], v[196:199], v[36:51]
	ds_read_b64_tr_b16 v[196:197], v178 offset:0x2400
	ds_read_b64_tr_b16 v[198:199], v178 offset:0x2c00
	v_mfma_f32_32x32x16_bf16 v[36:51], v[152:155], v[200:203], v[36:51]
	ds_read_b64_tr_b16 v[200:201], v178 offset:0x3400
	ds_read_b64_tr_b16 v[202:203], v178 offset:0x3c00
	s_waitcnt lgkmcnt(0)
	v_mfma_f32_32x32x16_bf16 v[20:35], v[140:143], v[188:191], v[20:35]
	ds_read_b64_tr_b16 v[188:189], v178 offset:0x600
	ds_read_b64_tr_b16 v[190:191], v178 offset:0xe00
	v_mfma_f32_32x32x16_bf16 v[20:35], v[144:147], v[192:195], v[20:35]
	ds_read_b64_tr_b16 v[192:193], v178 offset:0x1600
	ds_read_b64_tr_b16 v[194:195], v178 offset:0x1e00
	v_mfma_f32_32x32x16_bf16 v[20:35], v[148:151], v[196:199], v[20:35]
	ds_read_b64_tr_b16 v[196:197], v178 offset:0x2600
	ds_read_b64_tr_b16 v[198:199], v178 offset:0x2e00
	v_mfma_f32_32x32x16_bf16 v[20:35], v[152:155], v[200:203], v[20:35]
	ds_read_b64_tr_b16 v[200:201], v178 offset:0x3600
	ds_read_b64_tr_b16 v[202:203], v178 offset:0x3e00
	s_waitcnt lgkmcnt(0)
	v_mfma_f32_32x32x16_bf16 v[4:19], v[140:143], v[188:191], v[4:19]
	v_max_f32_e32 v140, v85, v85
	v_max_f32_e32 v141, v84, v84
	v_max_f32_e32 v140, v141, v140
	v_max3_f32 v140, v140, v86, v87
	v_max3_f32 v140, v140, v88, v89
	v_max3_f32 v140, v140, v90, v91
	v_max3_f32 v140, v140, v92, v93
	v_mfma_f32_32x32x16_bf16 v[4:19], v[144:147], v[192:195], v[4:19]
	v_max3_f32 v140, v140, v94, v95
	v_max3_f32 v140, v140, v96, v97
	v_max3_f32 v140, v140, v98, v99
	v_max3_f32 v140, v140, v68, v69
	v_max3_f32 v140, v140, v70, v71
	v_max3_f32 v140, v140, v72, v73
	v_max3_f32 v140, v140, v74, v75
	v_mfma_f32_32x32x16_bf16 v[4:19], v[148:151], v[196:199], v[4:19]
	v_max3_f32 v140, v140, v76, v77
	v_max3_f32 v140, v140, v78, v79
	v_max3_f32 v140, v140, v80, v81
	v_max3_f32 v140, v140, v82, v83
	v_mov_b32_e32 v141, v140
	s_nop 1
	v_permlane32_swap_b32_e32 v140, v141
	v_mfma_f32_32x32x16_bf16 v[4:19], v[152:155], v[200:203], v[4:19]
	v_max_f32_e32 v141, v141, v141
	v_max_f32_e32 v140, v140, v140
	v_max_f32_e32 v140, v140, v141
	v_sub_f32_e32 v141, v140, v185
	v_cmp_ge_f32_e32 vcc, s58, v141
	s_waitcnt lgkmcnt(0)
	s_barrier
	s_waitcnt vmcnt(0)
	s_cmp_eq_u64 vcc, exec
	s_cselect_b64 s[14:15], -1, 0
	s_waitcnt vmcnt(0)
	ds_write_b128 v179, v[212:215]
	ds_write_b128 v180, v[216:219]
	ds_write_b128 v183, v[220:223] offset:32768
	s_and_saveexec_b64 s[42:43], s[12:13]
	ds_write_b128 v186, v[224:227] offset:32768
	s_or_b64 exec, exec, s[42:43]
	v_max_f32_e32 v128, v185, v185
	v_max_f32_e32 v128, v128, v140
	v_sub_f32_e32 v129, v185, v128
	v_mul_f32_e32 v129, 0x3dd53b94, v129
	v_exp_f32_e32 v129, v129
	s_nop 0
	v_cndmask_b32_e64 v188, v129, 1.0, s[14:15]
	v_cmp_gt_f32_e32 vcc, 1.0, v188
	s_cbranch_vccz .LBB0_2422
	s_and_saveexec_b64 s[42:43], s[10:11]
	ds_write_b32 v175, v188 offset:57472
	s_or_b64 exec, exec, s[42:43]
	s_waitcnt lgkmcnt(0)
	v_add_u32_e32 v129, v157, v174
	ds_read_b128 v[130:133], v129 offset:57568
	ds_read_b128 v[134:137], v129 offset:57536
	ds_read_b128 v[138:141], v129 offset:57504
	ds_read_b128 v[142:145], v129 offset:57472
	s_waitcnt lgkmcnt(3)
	v_pk_mul_f32 v[64:65], v[64:65], v[130:131]
	s_waitcnt lgkmcnt(2)
	v_pk_mul_f32 v[60:61], v[60:61], v[134:135]
	s_waitcnt lgkmcnt(1)
	v_pk_mul_f32 v[56:57], v[56:57], v[138:139]
	v_pk_mul_f32 v[66:67], v[66:67], v[132:133]
	v_pk_mul_f32 v[62:63], v[62:63], v[136:137]
	v_pk_mul_f32 v[58:59], v[58:59], v[140:141]
	s_waitcnt lgkmcnt(0)
	v_pk_mul_f32 v[54:55], v[54:55], v[144:145]
	v_pk_mul_f32 v[52:53], v[52:53], v[142:143]
	v_pk_mul_f32 v[48:49], v[48:49], v[130:131]
	v_pk_mul_f32 v[44:45], v[44:45], v[134:135]
	v_pk_mul_f32 v[40:41], v[40:41], v[138:139]
	v_pk_mul_f32 v[50:51], v[50:51], v[132:133]
	v_pk_mul_f32 v[46:47], v[46:47], v[136:137]
	v_pk_mul_f32 v[42:43], v[42:43], v[140:141]
	v_pk_mul_f32 v[38:39], v[38:39], v[144:145]
	v_pk_mul_f32 v[36:37], v[36:37], v[142:143]
	v_pk_mul_f32 v[32:33], v[32:33], v[130:131]
	v_pk_mul_f32 v[28:29], v[28:29], v[134:135]
	v_pk_mul_f32 v[24:25], v[24:25], v[138:139]
	v_pk_mul_f32 v[34:35], v[34:35], v[132:133]
	v_pk_mul_f32 v[30:31], v[30:31], v[136:137]
	v_pk_mul_f32 v[26:27], v[26:27], v[140:141]
	v_pk_mul_f32 v[22:23], v[22:23], v[144:145]
	v_pk_mul_f32 v[20:21], v[20:21], v[142:143]
	v_pk_mul_f32 v[16:17], v[16:17], v[130:131]
	v_pk_mul_f32 v[12:13], v[12:13], v[134:135]
	v_pk_mul_f32 v[8:9], v[8:9], v[138:139]
	v_pk_mul_f32 v[18:19], v[18:19], v[132:133]
	v_pk_mul_f32 v[14:15], v[14:15], v[136:137]
	v_pk_mul_f32 v[10:11], v[10:11], v[140:141]
	v_pk_mul_f32 v[6:7], v[6:7], v[144:145]
	v_pk_mul_f32 v[4:5], v[4:5], v[142:143]

.Lattn_ldB_skip:
	s_or_b64 exec, exec, s[14:15]
	s_nop 1
	ds_read_b128 v[194:197], v181
	ds_read_b128 v[202:205], v181 offset:6144
	ds_read_b128 v[198:201], v182
	ds_read_b128 v[206:209], v182 offset:6144
	v_exp_f32_e32 v193, v140
	v_add_f32_e32 v140, 0, v131
	v_add_f32_e32 v140, v134, v140
	v_add_f32_e32 v140, v135, v140
	v_add_f32_e32 v140, v139, v140
	s_waitcnt lgkmcnt(1)
	v_mfma_scale_f32_32x32x64_f8f6f4 v[84:99], v[194:201], v[116:123], 0, v170, v170 op_sel_hi:[0,0,0]
	s_waitcnt lgkmcnt(0)
	v_mfma_scale_f32_32x32x64_f8f6f4 v[68:83], v[202:209], v[116:123], 0, v170, v170 op_sel_hi:[0,0,0]
	ds_read_b128 v[194:197], v181 offset:64
	ds_read_b128 v[202:205], v181 offset:6208
	ds_read_b128 v[198:201], v182 offset:64
	ds_read_b128 v[206:209], v182 offset:6208
	v_add_f32_e32 v140, v142, v140
	v_add_f32_e32 v140, v143, v140
	v_add_f32_e32 v140, v144, v140
	v_add_f32_e32 v140, v145, v140
	v_add_f32_e32 v140, v128, v140
	s_waitcnt lgkmcnt(1)
	v_mfma_scale_f32_32x32x64_f8f6f4 v[84:99], v[194:201], v[108:115], v[84:99], v170, v170 op_sel_hi:[0,0,0]
	s_waitcnt lgkmcnt(0)
	v_mfma_scale_f32_32x32x64_f8f6f4 v[68:83], v[202:209], v[108:115], v[68:83], v170, v170 op_sel_hi:[0,0,0]
	ds_read_b128 v[194:197], v181 offset:128
	ds_read_b128 v[202:205], v181 offset:6272
	ds_read_b128 v[198:201], v182 offset:128
	ds_read_b128 v[206:209], v182 offset:6272
	v_add_f32_e32 v140, v129, v140
	v_add_f32_e32 v140, v130, v140
	v_add_f32_e32 v140, v132, v140
	v_add_f32_e32 v140, v133, v140
	s_waitcnt lgkmcnt(1)
	v_mfma_scale_f32_32x32x64_f8f6f4 v[84:99], v[194:201], v[100:107], v[84:99], v170, v170 op_sel_hi:[0,0,0]
	v_exp_f32_e32 v194, v141
	v_add_f32_e32 v140, v136, v140
	v_exp_f32_e32 v195, v146
	v_add_f32_e32 v140, v137, v140
	v_exp_f32_e32 v196, v148
	v_add_f32_e32 v140, v147, v140
	v_exp_f32_e32 v197, v149
	v_add_f32_e32 v140, v193, v140
	v_exp_f32_e32 v150, v150
	v_add_f32_e32 v140, v194, v140
	v_exp_f32_e32 v151, v151
	v_add_f32_e32 v140, v195, v140
	v_exp_f32_e32 v152, v152
	v_add_f32_e32 v140, v196, v140
	v_exp_f32_e32 v153, v153
	v_add_f32_e32 v140, v197, v140
	v_exp_f32_e32 v154, v154
	v_add_f32_e32 v140, v150, v140
	v_exp_f32_e32 v155, v155
	v_add_f32_e32 v140, v151, v140
	v_exp_f32_e32 v198, v189
	v_add_f32_e32 v140, v152, v140
	v_exp_f32_e32 v199, v190
	v_add_f32_e32 v140, v153, v140
	v_exp_f32_e32 v191, v191
	v_add_f32_e32 v140, v154, v140
	v_exp_f32_e32 v192, v192
	v_add_f32_e32 v140, v155, v140
	v_exp_f32_e32 v138, v138
	v_add_f32_e32 v140, v198, v140
	v_add_f32_e32 v140, v199, v140
	v_add_f32_e32 v140, v191, v140
	v_add_f32_e32 v140, v192, v140
	v_add_f32_e32 v189, v138, v140
	v_mov_b32_e32 v190, v189
	v_cvt_pk_bf16_f32 v140, v131, v134
	v_cvt_pk_bf16_f32 v141, v135, v139
	v_cvt_pk_bf16_f32 v142, v142, v143
	v_cvt_pk_bf16_f32 v143, v144, v145
	v_cvt_pk_bf16_f32 v144, v128, v129
	v_cvt_pk_bf16_f32 v145, v130, v132
	v_cvt_pk_bf16_f32 v146, v133, v136
	v_cvt_pk_bf16_f32 v147, v137, v147
	v_cvt_pk_bf16_f32 v148, v193, v194
	v_cvt_pk_bf16_f32 v149, v195, v196
	v_cvt_pk_bf16_f32 v150, v197, v150
	v_cvt_pk_bf16_f32 v151, v151, v152
	v_cvt_pk_bf16_f32 v152, v153, v154
	v_cvt_pk_bf16_f32 v153, v155, v198
	v_cvt_pk_bf16_f32 v154, v199, v191
	v_cvt_pk_bf16_f32 v155, v192, v138
	s_waitcnt lgkmcnt(0)
	v_mfma_scale_f32_32x32x64_f8f6f4 v[68:83], v[202:209], v[100:107], v[68:83], v170, v170 op_sel_hi:[0,0,0]
	v_permlane32_swap_b32_e32 v189, v190
	v_permlane32_swap_b32_e32 v140, v142
	v_permlane32_swap_b32_e32 v141, v143
	v_permlane32_swap_b32_e32 v144, v146
	v_permlane32_swap_b32_e32 v145, v147
	v_permlane32_swap_b32_e32 v148, v150
	v_permlane32_swap_b32_e32 v149, v151
	v_permlane32_swap_b32_e32 v152, v154
	v_permlane32_swap_b32_e32 v153, v155
	ds_read_b64_tr_b16 v[164:165], v176 offset:0
	ds_read_b64_tr_b16 v[166:167], v176 offset:0x800
	ds_read_b64_tr_b16 v[192:193], v176 offset:0x1000
	ds_read_b64_tr_b16 v[194:195], v176 offset:0x1800
	ds_read_b64_tr_b16 v[196:197], v176 offset:0x2000
	ds_read_b64_tr_b16 v[198:199], v176 offset:0x2800
	ds_read_b64_tr_b16 v[200:201], v176 offset:0x3000
	ds_read_b64_tr_b16 v[202:203], v176 offset:0x3800
	s_waitcnt lgkmcnt(0)
	s_nop 0
	v_mfma_f32_32x32x16_bf16 v[52:67], v[140:143], v[164:167], v[52:67]
	ds_read_b64_tr_b16 v[164:165], v176 offset:0x200
	ds_read_b64_tr_b16 v[166:167], v176 offset:0xa00
	v_mfma_f32_32x32x16_bf16 v[52:67], v[144:147], v[192:195], v[52:67]
	ds_read_b64_tr_b16 v[192:193], v176 offset:0x1200
	ds_read_b64_tr_b16 v[194:195], v176 offset:0x1a00
	v_mfma_f32_32x32x16_bf16 v[52:67], v[148:151], v[196:199], v[52:67]
	ds_read_b64_tr_b16 v[196:197], v176 offset:0x2200
	ds_read_b64_tr_b16 v[198:199], v176 offset:0x2a00
	v_mfma_f32_32x32x16_bf16 v[52:67], v[152:155], v[200:203], v[52:67]
	ds_read_b64_tr_b16 v[200:201], v176 offset:0x3200
	ds_read_b64_tr_b16 v[202:203], v176 offset:0x3a00
	s_waitcnt lgkmcnt(0)
	v_mfma_f32_32x32x16_bf16 v[36:51], v[140:143], v[164:167], v[36:51]
	ds_read_b64_tr_b16 v[164:165], v176 offset:0x400
	ds_read_b64_tr_b16 v[166:167], v176 offset:0xc00
	v_mfma_f32_32x32x16_bf16 v[36:51], v[144:147], v[192:195], v[36:51]
	ds_read_b64_tr_b16 v[192:193], v176 offset:0x1400
	ds_read_b64_tr_b16 v[194:195], v176 offset:0x1c00
	v_mfma_f32_32x32x16_bf16 v[36:51], v[148:151], v[196:199], v[36:51]
	ds_read_b64_tr_b16 v[196:197], v176 offset:0x2400
	ds_read_b64_tr_b16 v[198:199], v176 offset:0x2c00
	v_mfma_f32_32x32x16_bf16 v[36:51], v[152:155], v[200:203], v[36:51]
	ds_read_b64_tr_b16 v[200:201], v176 offset:0x3400
	ds_read_b64_tr_b16 v[202:203], v176 offset:0x3c00
	s_waitcnt lgkmcnt(0)
	v_mfma_f32_32x32x16_bf16 v[20:35], v[140:143], v[164:167], v[20:35]
	ds_read_b64_tr_b16 v[164:165], v176 offset:0x600
	ds_read_b64_tr_b16 v[166:167], v176 offset:0xe00
	v_mfma_f32_32x32x16_bf16 v[20:35], v[144:147], v[192:195], v[20:35]
	ds_read_b64_tr_b16 v[192:193], v176 offset:0x1600
	ds_read_b64_tr_b16 v[194:195], v176 offset:0x1e00
	v_mfma_f32_32x32x16_bf16 v[20:35], v[148:151], v[196:199], v[20:35]
	ds_read_b64_tr_b16 v[196:197], v176 offset:0x2600
	ds_read_b64_tr_b16 v[198:199], v176 offset:0x2e00
	v_mfma_f32_32x32x16_bf16 v[20:35], v[152:155], v[200:203], v[20:35]
	ds_read_b64_tr_b16 v[200:201], v176 offset:0x3600
	ds_read_b64_tr_b16 v[202:203], v176 offset:0x3e00
	s_waitcnt lgkmcnt(0)
	v_mfma_f32_32x32x16_bf16 v[4:19], v[140:143], v[164:167], v[4:19]
	v_max_f32_e32 v140, v85, v85
	v_max_f32_e32 v141, v84, v84
	v_max_f32_e32 v140, v141, v140
	v_max3_f32 v140, v140, v86, v87
	v_max3_f32 v140, v140, v88, v89
	v_max3_f32 v140, v140, v90, v91
	v_max3_f32 v140, v140, v92, v93
	v_mfma_f32_32x32x16_bf16 v[4:19], v[144:147], v[192:195], v[4:19]
	v_max3_f32 v140, v140, v94, v95
	v_max3_f32 v140, v140, v96, v97
	v_max3_f32 v140, v140, v98, v99
	v_max3_f32 v140, v140, v68, v69
	v_max3_f32 v140, v140, v70, v71
	v_max3_f32 v140, v140, v72, v73
	v_max3_f32 v140, v140, v74, v75
	v_mfma_f32_32x32x16_bf16 v[4:19], v[148:151], v[196:199], v[4:19]
	v_max3_f32 v140, v140, v76, v77
	v_max3_f32 v140, v140, v78, v79
	v_max3_f32 v140, v140, v80, v81
	v_max3_f32 v140, v140, v82, v83
	v_mov_b32_e32 v141, v140
	s_nop 1
	v_permlane32_swap_b32_e32 v140, v141
	v_mfma_f32_32x32x16_bf16 v[4:19], v[152:155], v[200:203], v[4:19]
	v_max_f32_e32 v141, v141, v141
	v_max_f32_e32 v140, v140, v140
	v_max_f32_e32 v140, v140, v141
	v_sub_f32_e32 v141, v140, v185
	v_cmp_ge_f32_e32 vcc, s58, v141
	s_waitcnt lgkmcnt(0)
	s_barrier
	s_waitcnt vmcnt(0)
	s_cmp_eq_u64 vcc, exec
	s_cselect_b64 s[14:15], -1, 0
	s_waitcnt vmcnt(0)
	ds_write_b128 v179, v[212:215] offset:16384
	ds_write_b128 v180, v[216:219] offset:16384
	ds_write_b128 v183, v[220:223] offset:45056
	s_and_saveexec_b64 s[42:43], s[12:13]
	ds_write_b128 v186, v[224:227] offset:45056
	s_or_b64 exec, exec, s[42:43]
	v_max_f32_e32 v128, v185, v185
	v_max_f32_e32 v128, v128, v140
	v_sub_f32_e32 v129, v185, v128
	v_mul_f32_e32 v129, 0x3dd53b94, v129
	v_exp_f32_e32 v129, v129
	s_nop 0
	v_cndmask_b32_e64 v144, v129, 1.0, s[14:15]
	v_cmp_gt_f32_e32 vcc, 1.0, v144
	s_cbranch_vccz .LBB0_2430
	s_and_saveexec_b64 s[42:43], s[10:11]
	ds_write_b32 v175, v144 offset:57472
	s_or_b64 exec, exec, s[42:43]
	s_waitcnt lgkmcnt(0)
	v_add_u32_e32 v129, v157, v174
	ds_read_b128 v[130:133], v129 offset:57568
	ds_read_b128 v[134:137], v129 offset:57536
	ds_read_b128 v[138:141], v129 offset:57504
	ds_read_b128 v[146:149], v129 offset:57472
	s_waitcnt lgkmcnt(3)
	v_pk_mul_f32 v[64:65], v[64:65], v[130:131]
	s_waitcnt lgkmcnt(2)
	v_pk_mul_f32 v[60:61], v[60:61], v[134:135]
	s_waitcnt lgkmcnt(1)
	v_pk_mul_f32 v[56:57], v[56:57], v[138:139]
	v_pk_mul_f32 v[66:67], v[66:67], v[132:133]
	v_pk_mul_f32 v[62:63], v[62:63], v[136:137]
	v_pk_mul_f32 v[58:59], v[58:59], v[140:141]
	s_waitcnt lgkmcnt(0)
	v_pk_mul_f32 v[54:55], v[54:55], v[148:149]
	v_pk_mul_f32 v[52:53], v[52:53], v[146:147]
	v_pk_mul_f32 v[48:49], v[48:49], v[130:131]
	v_pk_mul_f32 v[44:45], v[44:45], v[134:135]
	v_pk_mul_f32 v[40:41], v[40:41], v[138:139]
	v_pk_mul_f32 v[50:51], v[50:51], v[132:133]
	v_pk_mul_f32 v[46:47], v[46:47], v[136:137]
	v_pk_mul_f32 v[42:43], v[42:43], v[140:141]
	v_pk_mul_f32 v[38:39], v[38:39], v[148:149]
	v_pk_mul_f32 v[36:37], v[36:37], v[146:147]
	v_pk_mul_f32 v[32:33], v[32:33], v[130:131]
	v_pk_mul_f32 v[28:29], v[28:29], v[134:135]
	v_pk_mul_f32 v[24:25], v[24:25], v[138:139]
	v_pk_mul_f32 v[34:35], v[34:35], v[132:133]
	v_pk_mul_f32 v[30:31], v[30:31], v[136:137]
	v_pk_mul_f32 v[26:27], v[26:27], v[140:141]
	v_pk_mul_f32 v[22:23], v[22:23], v[148:149]
	v_pk_mul_f32 v[20:21], v[20:21], v[146:147]
	v_pk_mul_f32 v[16:17], v[16:17], v[130:131]
	v_pk_mul_f32 v[12:13], v[12:13], v[134:135]
	v_pk_mul_f32 v[8:9], v[8:9], v[138:139]
	v_pk_mul_f32 v[18:19], v[18:19], v[132:133]
	v_pk_mul_f32 v[14:15], v[14:15], v[136:137]
	v_pk_mul_f32 v[10:11], v[10:11], v[140:141]
	v_pk_mul_f32 v[6:7], v[6:7], v[148:149]
	v_pk_mul_f32 v[4:5], v[4:5], v[146:147]
